# XCD-local grid barriers after phases 6 and 7 (norm-1 rows remapped to the XCD that produces and consumes them); no global L2 writeback there
# speedup vs baseline: 1.1702x; 1.1702x over previous
.LBB0_821:
	s_andn2_saveexec_b64 s[0:1], s[8:9]
	s_cbranch_execz .LBB0_841
	s_mov_b64 s[8:9], exec
	s_branch .LBB0_838
	buffer_wbl2 sc1
	s_waitcnt lgkmcnt(0)
	s_waitcnt vmcnt(0)
	v_mbcnt_lo_u32_b32 v1, s8, 0
	v_mbcnt_hi_u32_b32 v1, s9, v1
	v_cmp_eq_u32_e32 vcc, 0, v1
	s_and_saveexec_b64 s[10:11], vcc
	s_cbranch_execz .LBB0_824
	s_bcnt1_i32_b64 s0, s[8:9]
	v_mov_b32_e32 v2, 0xfd2c000
	v_mov_b32_e32 v3, s0
	global_atomic_add v2, v2, v3, s[58:59] offset:1024 sc0

.LBB0_841:
	s_or_b64 exec, exec, s[4:5]
	s_cmpk_lt_i32 s76, 0x200
	s_cselect_b64 s[12:13], -1, 0
	s_cmpk_gt_i32 s76, 0x1ff
	s_waitcnt lgkmcnt(0)
	s_barrier
	s_cbranch_scc1 .LBB0_846
	s_add_u32 s2, s58, 0xfd11000
	s_addc_u32 s21, s59, 0
	s_add_u32 s14, s58, 0xcd1000
	v_mbcnt_lo_u32_b32 v0, -1, 0
	s_addc_u32 s15, s59, 0
	v_mbcnt_hi_u32_b32 v48, -1, v0
	s_add_u32 s16, s58, 0xb0d1000
	s_mov_b32 s0, 0x358637bd
	v_and_b32_e32 v0, 64, v48
	s_addc_u32 s17, s59, 0
	s_mov_b64 s[18:19], 0x1000
	s_movk_i32 s24, 0x1000
	v_mov_b32_e32 v33, 0
	s_mov_b32 s20, 0x3a800000
	v_mov_b64_e32 v[34:35], s[0:1]
	s_mov_b32 s25, 0x800000
	v_add_u32_e32 v49, 64, v0
	v_xor_b32_e32 v50, 32, v48
	v_xor_b32_e32 v51, 16, v48
	v_xor_b32_e32 v52, 8, v48
	v_xor_b32_e32 v53, 4, v48
	v_xor_b32_e32 v54, 2, v48
	v_xor_b32_e32 v55, 1, v48
	s_and_b32 s0, s76, 7
	s_lshl_b32 s0, s0, 6
	s_lshr_b32 s1, s76, 6
	s_lshl_b32 s1, s1, 3
	s_or_b32 s0, s0, s1
	s_bfe_u32 s1, s76, 0x30003
	s_or_b32 s26, s0, s1
